# F1 T2 loop: dead global-address arithmetic of the replaced 8-byte stores removed (7 VALU per iteration), wait states kept with s_nop
# speedup vs baseline: 1.0042x; 1.0042x over previous
.LBB0_216:
	ds_read_b128 v[134:137], v133
	ds_read_b128 v[138:141], v133 offset:64
	ds_read_b128 v[142:145], v133 offset:17408
	ds_read_b128 v[150:153], v133 offset:17472
	ds_read_b128 v[154:157], v133 offset:128
	ds_read_b128 v[158:161], v133 offset:192
	ds_read_b128 v[162:165], v133 offset:17536
	ds_read_b128 v[166:169], v133 offset:17600
	s_waitcnt lgkmcnt(7)
	v_mfma_f32_16x16x32_bf16 v[134:137], v[50:53], v[134:137], 0
	s_cmp_eq_u32 s36, 0
	s_cselect_b64 vcc, -1, 0
	s_cmpk_eq_i32 s36, 0x400
	s_waitcnt lgkmcnt(5)
	v_mfma_f32_16x16x32_bf16 v[142:145], v[50:53], v[142:145], 0
	s_cselect_b64 s[0:1], -1, 0
	s_cmpk_eq_i32 s36, 0x800
	s_cselect_b64 s[4:5], -1, 0
	v_mfma_f32_16x16x32_bf16 v[134:137], v[54:57], v[138:141], v[134:137]
	s_waitcnt lgkmcnt(4)
	v_mfma_f32_16x16x32_bf16 v[138:141], v[54:57], v[150:153], v[142:145]
	s_addk_i32 s36, 0x400
	v_add_u32_e32 v133, 0x1100, v133
	s_cmpk_lg_i32 s36, 0x1000
	s_waitcnt lgkmcnt(1)
	v_mfma_f32_16x16x32_bf16 v[138:141], v[58:61], v[162:165], v[138:141]
	v_cndmask_b32_e64 v145, v123, v121, s[4:5]
	v_cndmask_b32_e64 v144, v115, v113, s[4:5]
	v_cndmask_b32_e64 v145, v145, v119, s[0:1]
	v_mfma_f32_16x16x32_bf16 v[134:137], v[58:61], v[154:157], v[134:137]
	v_cndmask_b32_e64 v144, v144, v111, s[0:1]
	v_cndmask_b32_e32 v150, v145, v117, vcc
	s_waitcnt lgkmcnt(0)
	v_mfma_f32_16x16x32_bf16 v[138:141], v[62:65], v[166:169], v[138:141]
	v_cndmask_b32_e32 v144, v144, v109, vcc
	v_mfma_f32_16x16x32_bf16 v[134:137], v[62:65], v[158:161], v[134:137]
	s_nop 5
	v_pk_mul_f32 v[152:153], v[150:151], v[138:139] op_sel_hi:[0,1]
	v_pk_mul_f32 v[156:157], v[150:151], v[140:141] op_sel_hi:[0,1]
	s_nop 1
	v_pk_mul_f32 v[154:155], v[150:151], v[134:135] op_sel_hi:[0,1]
	v_pk_mul_f32 v[150:151], v[150:151], v[136:137] op_sel_hi:[0,1]
	v_pk_fma_f32 v[134:135], v[144:145], v[134:135], v[152:153] op_sel_hi:[0,1,1]
	v_pk_fma_f32 v[136:137], v[144:145], v[136:137], v[156:157] op_sel_hi:[0,1,1]
	v_pk_fma_f32 v[138:139], v[144:145], v[138:139], v[154:155] op_sel_hi:[0,1,1] neg_lo:[0,0,1] neg_hi:[0,0,1]
	v_pk_fma_f32 v[140:141], v[144:145], v[140:141], v[150:151] op_sel_hi:[0,1,1] neg_lo:[0,0,1] neg_hi:[0,0,1]
	v_cvt_pk_bf16_f32 v134, v134, v135
	v_cvt_pk_bf16_f32 v135, v136, v137
	v_cvt_pk_bf16_f32 v136, v138, v139
	v_cvt_pk_bf16_f32 v137, v140, v141
	v_add_u32_e32 v200, v203, v133
	v_add_u32_e32 v205, s37, v200
	ds_write_b64 v200, v[134:135]
	ds_write_b64 v205, v[136:137]
	s_cbranch_scc1 .LBB0_216
	s_waitcnt lgkmcnt(0)
	s_barrier
	ds_read_b128 v[184:187], v204
	ds_read_b128 v[188:191], v204 offset:1088
	ds_read_b128 v[192:195], v206
	ds_read_b128 v[196:199], v206 offset:1088
	s_and_b32 s6, s24, 1
	v_add_u32_e32 v182, s6, v180
	v_lshlrev_b32_e32 v182, 10, v182
	v_lshl_add_u32 v182, v181, 1, v182
	v_add_u32_e32 v183, 0x40000, v182
	s_waitcnt lgkmcnt(0)
	global_store_dwordx4 v182, v[184:187], s[14:15]
	global_store_dwordx4 v183, v[188:191], s[14:15]
	global_store_dwordx4 v182, v[192:195], s[12:13]
	global_store_dwordx4 v183, v[196:199], s[12:13]
	s_mov_b32 s4, 1
	s_mov_b64 s[0:1], 0
	s_and_b64 vcc, exec, s[24:25]
	s_cbranch_vccz .LBB0_215
	s_add_i32 s26, s26, s28
	s_and_b64 vcc, exec, s[22:23]
	s_mov_b32 s1, s31
	s_cbranch_vccz .LBB0_212
	s_waitcnt vmcnt(5)
	v_mov_b32_e32 v2, v67
